# dil_combine loop fully unrolled, all 48 loads in flight
# speedup vs baseline: 1.0016x; 1.0016x over previous
.LBB0_588:
	v_add_u32_e32 v113, v161, v159
	v_sub_u32_e32 v115, v159, v89
	v_sub_u32_e32 v124, v159, v88
	v_sub_u32_e32 v138, v159, v91
	v_sub_u32_e32 v139, v159, v90
	v_sub_u32_e32 v140, v159, v93
	v_sub_u32_e32 v141, v159, v92
	v_sub_u32_e32 v142, v159, v95
	v_sub_u32_e32 v143, v159, v94
	v_cvt_f32_u32_e32 v39, v113
	v_cvt_f32_u32_e32 v40, v124
	v_cvt_f32_u32_e32 v41, v115
	v_cvt_f32_u32_e32 v42, v139
	v_cvt_f32_u32_e32 v43, v138
	v_cvt_f32_u32_e32 v44, v141
	v_cvt_f32_u32_e32 v45, v140
	v_cvt_f32_u32_e32 v46, v143
	v_cvt_f32_u32_e32 v47, v142
	ds_read_b128 v[32:35], v162
	ds_read_b128 v[84:87], v162 offset:32
	ds_read_b128 v[102:105], v162 offset:64
	ds_read_b128 v[106:109], v162 offset:96
	v_add_u32_e32 v36, 0xffffdc00, v160
	v_add_u32_e32 v37, 0xfffffc00, v160
	v_add_u32_e32 v38, 0xffffe000, v160
	ds_read_b64_tr_b16 v[120:121], v36
	ds_read_b64_tr_b16 v[122:123], v36 offset:512
	ds_read_b64_tr_b16 v[116:117], v37
	ds_read_b64_tr_b16 v[118:119], v37 offset:512
	s_waitcnt lgkmcnt(0)
	ds_read_b64_tr_b16 v[130:131], v38
	ds_read_b64_tr_b16 v[132:133], v38 offset:512
	ds_read_b64_tr_b16 v[126:127], v160
	ds_read_b64_tr_b16 v[128:129], v160 offset:512
	s_waitcnt lgkmcnt(0)
	v_mul_f32_e32 v154, v151, v39
	v_mul_f32_e32 v155, v151, v40
	v_mul_f32_e32 v163, v151, v41
	v_mul_f32_e32 v164, v151, v42
	v_mul_f32_e32 v165, v151, v43
	v_mul_f32_e32 v166, v151, v44
	v_mul_f32_e32 v167, v151, v45
	v_mul_f32_e32 v168, v151, v46
	v_mul_f32_e32 v169, v151, v47
	s_waitcnt lgkmcnt(3)
	v_mfma_f32_32x32x16_bf16 v[32:47], v[32:35], v[64:67], 0
	v_add_u32_e32 v152, -1, v113
	v_sub_u32_e32 v144, v159, v97
	v_sub_u32_e32 v145, v159, v96
	v_sub_u32_e32 v146, v159, v99
	v_sub_u32_e32 v147, v159, v98
	v_sub_u32_e32 v148, v159, v101
	v_sub_u32_e32 v149, v159, v100
	s_waitcnt lgkmcnt(2)
	v_mfma_f32_32x32x16_bf16 v[32:47], v[84:87], v[68:71], v[32:47]
	v_cvt_f32_u32_e32 v153, v152
	v_cvt_f32_u32_e32 v110, v145
	v_cvt_f32_u32_e32 v111, v144
	v_cvt_f32_u32_e32 v134, v147
	v_cvt_f32_u32_e32 v135, v146
	v_cvt_f32_u32_e32 v136, v149
	v_cvt_f32_u32_e32 v137, v148
	s_waitcnt lgkmcnt(1)
	v_mfma_f32_32x32x16_bf16 v[32:47], v[102:105], v[72:75], v[32:47]
	v_mul_f32_e32 v153, v151, v153
	v_mul_f32_e32 v170, v151, v110
	v_mul_f32_e32 v171, v151, v111
	v_mul_f32_e32 v173, v151, v134
	v_mul_f32_e32 v174, v151, v135
	v_mul_f32_e32 v136, v151, v136
	v_mul_f32_e32 v137, v151, v137
	s_waitcnt lgkmcnt(0)
	v_mfma_f32_32x32x16_bf16 v[32:47], v[106:109], v[76:79], v[32:47]
	v_exp_f32_e32 v154, v154
	v_exp_f32_e32 v110, v155
	v_exp_f32_e32 v111, v163
	v_exp_f32_e32 v84, v164
	v_exp_f32_e32 v85, v165
	v_exp_f32_e32 v86, v166
	v_exp_f32_e32 v87, v167
	v_exp_f32_e32 v153, v153
	v_exp_f32_e32 v134, v168
	v_exp_f32_e32 v135, v169
	v_exp_f32_e32 v102, v170
	v_exp_f32_e32 v103, v171
	v_exp_f32_e32 v104, v173
	v_exp_f32_e32 v105, v174
	v_exp_f32_e32 v136, v136
	v_exp_f32_e32 v137, v137
	v_mul_f32_e32 v106, v154, v32
	v_mul_f32_e32 v107, v153, v33
	v_cmp_lt_i32_e32 vcc, -1, v152
	v_pk_mul_f32 v[32:33], v[110:111], v[34:35]
	v_pk_mul_f32 v[34:35], v[84:85], v[36:37]
	v_pk_mul_f32 v[36:37], v[86:87], v[38:39]
	v_pk_mul_f32 v[38:39], v[134:135], v[40:41]
	v_pk_mul_f32 v[40:41], v[102:103], v[42:43]
	v_pk_mul_f32 v[42:43], v[104:105], v[44:45]
	v_pk_mul_f32 v[44:45], v[136:137], v[46:47]
	v_cmp_lt_i32_e64 s[0:1], -1, v113
	v_cndmask_b32_e32 v47, 0, v107, vcc
	v_cvt_pk_bf16_f32 v33, v32, v33
	v_cmp_lt_i32_e32 vcc, -1, v124
	v_cvt_pk_bf16_f32 v34, v34, v35
	v_cvt_pk_bf16_f32 v35, v36, v37
	v_cndmask_b32_e64 v46, 0, v106, s[0:1]
	v_cmp_lt_i32_e64 s[0:1], -1, v139
	v_cmp_lt_i32_e64 s[4:5], -1, v141
	v_cvt_pk_bf16_f32 v36, v38, v39
	v_cvt_pk_bf16_f32 v37, v40, v41
	v_cvt_pk_bf16_f32 v39, v44, v45
	v_lshrrev_b32_e32 v40, 16, v34
	v_cmp_lt_i32_e64 s[14:15], -1, v138
	v_lshrrev_b32_e32 v41, 16, v35
	v_cmp_lt_i32_e64 s[16:17], -1, v140
	v_cndmask_b32_e32 v45, 0, v33, vcc
	v_lshrrev_b32_e32 v33, 16, v33
	v_cmp_lt_i32_e32 vcc, -1, v115
	v_cndmask_b32_e64 v34, 0, v34, s[0:1]
	v_cndmask_b32_e64 v35, 0, v35, s[4:5]
	v_cndmask_b32_e32 v33, 0, v33, vcc
	v_cndmask_b32_e64 v40, 0, v40, s[14:15]
	v_cndmask_b32_e64 v41, 0, v41, s[16:17]
	v_cvt_pk_bf16_f32 v32, v46, v47
	v_perm_b32 v33, v33, v45, s3
	v_perm_b32 v34, v40, v34, s3
	v_perm_b32 v35, v41, v35, s3
	v_cmp_lt_i32_e64 s[6:7], -1, v143
	v_cvt_pk_bf16_f32 v38, v42, v43
	v_mfma_f32_32x32x16_bf16 v[0:15], v[120:123], v[32:35], v[0:15]
	v_cmp_lt_i32_e64 s[8:9], -1, v145
	v_cmp_lt_i32_e64 s[10:11], -1, v147
	v_cmp_lt_i32_e64 s[12:13], -1, v149
	v_lshrrev_b32_e32 v42, 16, v37
	v_cmp_lt_i32_e64 s[18:19], -1, v144
	v_lshrrev_b32_e32 v43, 16, v38
	v_cmp_lt_i32_e64 s[20:21], -1, v146
	v_mfma_f32_32x32x16_bf16 v[16:31], v[116:119], v[32:35], v[16:31]
	v_lshrrev_b32_e32 v44, 16, v39
	v_cmp_lt_i32_e64 s[22:23], -1, v148
	v_cndmask_b32_e64 v40, 0, v36, s[6:7]
	v_lshrrev_b32_e32 v36, 16, v36
	v_cmp_lt_i32_e32 vcc, -1, v142
	v_cndmask_b32_e64 v37, 0, v37, s[8:9]
	v_cndmask_b32_e64 v38, 0, v38, s[10:11]
	v_cndmask_b32_e64 v39, 0, v39, s[12:13]
	v_cndmask_b32_e32 v36, 0, v36, vcc
	v_cndmask_b32_e64 v33, 0, v42, s[18:19]
	v_cndmask_b32_e64 v34, 0, v43, s[20:21]
	v_cndmask_b32_e64 v35, 0, v44, s[22:23]
	v_perm_b32 v32, v36, v40, s3
	v_perm_b32 v33, v33, v37, s3
	v_perm_b32 v34, v34, v38, s3
	v_perm_b32 v35, v35, v39, s3
	s_add_i32 s2, s2, -1
	v_subrev_u32_e32 v159, 32, v159
	v_mfma_f32_32x32x16_bf16 v[0:15], v[130:133], v[32:35], v[0:15]
	v_add_u32_e32 v162, 0x1200, v162
	s_cmp_lg_u32 s2, 0
	v_add_u32_e32 v160, 0x800, v160
	v_mfma_f32_32x32x16_bf16 v[16:31], v[126:129], v[32:35], v[16:31]
	s_cbranch_scc1 .LBB0_588
	v_lshlrev_b64 v[32:33], 12, v[82:83]
	v_readlane_b32 s4, v254, 0
	v_lshlrev_b32_e32 v36, 11, v82
	v_and_b32_e32 v32, 0xfff00000, v32
	v_readlane_b32 s6, v254, 2
	v_readlane_b32 s7, v254, 3
	s_waitcnt vmcnt(0)
	v_lshlrev_b32_e32 v40, 16, v62
	v_and_b32_e32 v38, 0xffff0000, v62
	v_lshl_add_u64 v[34:35], s[6:7], 0, v[32:33]
	v_and_b32_e32 v32, 0x7f800, v36
	v_mul_f32_e32 v36, 0xbfb8aa3b, v40
	v_mul_f32_e32 v37, 0xbfb8aa3b, v38
	v_exp_f32_e32 v36, v36
	v_exp_f32_e32 v37, v37
	v_mov_b32_e32 v33, 0
	v_lshl_add_u64 v[34:35], v[34:35], 0, v[32:33]
	v_lshlrev_b32_e32 v45, 16, v61
	v_pk_add_f32 v[36:37], v[36:37], 1.0 op_sel_hi:[1,0]
	v_and_b32_e32 v46, 0xffff0000, v61
	v_div_scale_f32 v32, s[0:1], v37, v37, v38
	v_rcp_f32_e32 v39, v32
	v_lshlrev_b32_e32 v66, 16, v63
	v_and_b32_e32 v44, 0xffff0000, v63
	v_lshlrev_b32_e32 v71, 16, v58
	v_fma_f32 v41, -v32, v39, 1.0
	v_fmac_f32_e32 v39, v41, v39
	v_div_scale_f32 v41, vcc, v38, v37, v38
	v_mul_f32_e32 v42, v41, v39
	v_fma_f32 v43, -v32, v42, v41
	v_fmac_f32_e32 v42, v43, v39
	v_fma_f32 v32, -v32, v42, v41
	v_div_scale_f32 v41, s[0:1], v36, v36, v40
	v_rcp_f32_e32 v43, v41
	v_div_fmas_f32 v32, v32, v39, v42
	v_div_fixup_f32 v37, v32, v37, v38
	v_mul_f32_e32 v38, 0xbfb8aa3b, v45
	v_mul_f32_e32 v39, 0xbfb8aa3b, v46
	v_fma_f32 v32, -v41, v43, 1.0
	v_exp_f32_e32 v38, v38
	v_exp_f32_e32 v39, v39
	v_fmac_f32_e32 v43, v32, v43
	v_div_scale_f32 v32, vcc, v40, v36, v40
	v_mul_f32_e32 v42, v32, v43
	v_fma_f32 v47, -v41, v42, v32
	v_fmac_f32_e32 v42, v47, v43
	v_pk_add_f32 v[38:39], v[38:39], 1.0 op_sel_hi:[1,0]
	v_fma_f32 v32, -v41, v42, v32
	v_div_scale_f32 v41, s[0:1], v39, v39, v46
	v_rcp_f32_e32 v47, v41
	v_div_fmas_f32 v32, v32, v43, v42
	v_div_fixup_f32 v36, v32, v36, v40
	v_and_b32_e32 v58, 0xffff0000, v58
	v_fma_f32 v32, -v41, v47, 1.0
	v_fmac_f32_e32 v47, v32, v47
	v_div_scale_f32 v32, vcc, v46, v39, v46
	v_mul_f32_e32 v40, v32, v47
	v_fma_f32 v42, -v41, v40, v32
	v_fmac_f32_e32 v40, v42, v47
	v_fma_f32 v32, -v41, v40, v32
	v_div_scale_f32 v41, s[0:1], v38, v38, v45
	v_rcp_f32_e32 v42, v41
	v_div_fmas_f32 v32, v32, v47, v40
	v_div_fixup_f32 v39, v32, v39, v46
	v_lshlrev_b32_e32 v78, 16, v59
	v_fma_f32 v32, -v41, v42, 1.0
	v_fmac_f32_e32 v42, v32, v42
	v_div_scale_f32 v32, vcc, v45, v38, v45
	v_mul_f32_e32 v40, v32, v42
	v_fma_f32 v43, -v41, v40, v32
	v_fmac_f32_e32 v40, v43, v42
	v_fma_f32 v32, -v41, v40, v32
	v_div_fmas_f32 v32, v32, v42, v40
	v_lshlrev_b32_e32 v42, 16, v60
	v_and_b32_e32 v43, 0xffff0000, v60
	v_mul_f32_e32 v40, 0xbfb8aa3b, v42
	v_mul_f32_e32 v41, 0xbfb8aa3b, v43
	v_exp_f32_e32 v40, v40
	v_exp_f32_e32 v41, v41
	v_div_fixup_f32 v38, v32, v38, v45
	v_and_b32_e32 v76, 0xffff0000, v59
	v_lshlrev_b32_e32 v77, 16, v57
	v_pk_add_f32 v[40:41], v[40:41], 1.0 op_sel_hi:[1,0]
	v_and_b32_e32 v57, 0xffff0000, v57
	v_div_scale_f32 v67, s[0:1], v41, v41, v43
	v_rcp_f32_e32 v68, v67
	s_waitcnt lgkmcnt(0)
	s_barrier
	v_fma_f32 v45, -v67, v68, 1.0
	v_fmac_f32_e32 v68, v45, v68
	v_div_scale_f32 v45, vcc, v43, v41, v43
	v_mul_f32_e32 v69, v45, v68
	v_fma_f32 v70, -v67, v69, v45
	v_fmac_f32_e32 v69, v70, v68
	v_fma_f32 v45, -v67, v69, v45
	v_div_scale_f32 v67, s[0:1], v40, v40, v42
	v_rcp_f32_e32 v70, v67
	v_div_fmas_f32 v45, v45, v68, v69
	v_div_fixup_f32 v41, v45, v41, v43
	ds_write2_b32 v172, v0, v1 offset1:1
	ds_write2_b32 v172, v2, v3 offset0:2 offset1:3
	ds_write2_b32 v172, v4, v5 offset0:8 offset1:9
	ds_write2_b32 v172, v6, v7 offset0:10 offset1:11
	ds_write2_b32 v172, v8, v9 offset0:16 offset1:17
	ds_write2_b32 v172, v10, v11 offset0:18 offset1:19
	ds_write2_b32 v172, v12, v13 offset0:24 offset1:25
	ds_write2_b32 v172, v14, v15 offset0:26 offset1:27
	ds_write2_b32 v172, v16, v17 offset0:32 offset1:33
	ds_write2_b32 v172, v18, v19 offset0:34 offset1:35
	ds_write2_b32 v172, v20, v21 offset0:40 offset1:41
	ds_write2_b32 v172, v22, v23 offset0:42 offset1:43
	ds_write2_b32 v172, v24, v25 offset0:48 offset1:49
	ds_write2_b32 v172, v26, v27 offset0:50 offset1:51
	ds_write2_b32 v172, v28, v29 offset0:56 offset1:57
	ds_write2_b32 v172, v30, v31 offset0:58 offset1:59
	v_fma_f32 v43, -v67, v70, 1.0
	v_fmac_f32_e32 v70, v43, v70
	v_div_scale_f32 v43, vcc, v42, v40, v42
	v_mul_f32_e32 v45, v43, v70
	v_fma_f32 v68, -v67, v45, v43
	v_fmac_f32_e32 v45, v68, v70
	v_fma_f32 v43, -v67, v45, v43
	v_div_fmas_f32 v43, v43, v70, v45
	v_div_fixup_f32 v40, v43, v40, v42
	v_mul_f32_e32 v42, 0xbfb8aa3b, v66
	v_mul_f32_e32 v43, 0xbfb8aa3b, v44
	v_exp_f32_e32 v42, v42
	v_exp_f32_e32 v43, v43
	s_waitcnt lgkmcnt(0)
	s_barrier
	v_pk_add_f32 v[42:43], v[42:43], 1.0 op_sel_hi:[1,0]
	v_lshlrev_b32_e32 v79, 16, v56
	v_div_scale_f32 v45, s[0:1], v43, v43, v44
	v_rcp_f32_e32 v67, v45
	global_load_dwordx4 v[16:19], v[80:81], off offset:48
	global_load_dwordx4 v[20:23], v[80:81], off offset:32
	global_load_dwordx4 v[24:27], v[80:81], off offset:16
	global_load_dwordx4 v[28:31], v[80:81], off
	global_load_dwordx4 v[0:3], v[80:81], off offset:112
	global_load_dwordx4 v[4:7], v[80:81], off offset:96
	global_load_dwordx4 v[8:11], v[80:81], off offset:80
	global_load_dwordx4 v[12:15], v[80:81], off offset:64
	v_and_b32_e32 v80, 0xffff0000, v56
	v_mul_f32_e32 v56, 0xbfb8aa3b, v79
	v_fma_f32 v68, -v45, v67, 1.0
	v_fmac_f32_e32 v67, v68, v67
	v_div_scale_f32 v68, vcc, v44, v43, v44
	v_mul_f32_e32 v69, v68, v67
	v_fma_f32 v70, -v45, v69, v68
	v_fmac_f32_e32 v69, v70, v67
	v_fma_f32 v45, -v45, v69, v68
	v_div_scale_f32 v68, s[0:1], v42, v42, v66
	v_rcp_f32_e32 v70, v68
	v_div_fmas_f32 v45, v45, v67, v69
	v_div_fixup_f32 v43, v45, v43, v44
	v_div_scale_f32 v67, vcc, v66, v42, v66
	v_fma_f32 v44, -v68, v70, 1.0
	v_fmac_f32_e32 v70, v44, v70
	v_mul_f32_e32 v69, v67, v70
	v_fma_f32 v44, -v68, v69, v67
	v_fmac_f32_e32 v69, v44, v70
	v_mul_f32_e32 v44, 0xbfb8aa3b, v71
	v_mul_f32_e32 v45, 0xbfb8aa3b, v58
	v_exp_f32_e32 v44, v44
	v_exp_f32_e32 v45, v45
	v_fma_f32 v67, -v68, v69, v67
	v_div_fmas_f32 v67, v67, v70, v69
	v_div_fixup_f32 v42, v67, v42, v66
	v_pk_add_f32 v[44:45], v[44:45], 1.0 op_sel_hi:[1,0]
	v_lshlrev_b32_e32 v83, 16, v54
	v_div_scale_f32 v68, s[0:1], v45, v45, v58
	v_rcp_f32_e32 v69, v68
	v_and_b32_e32 v54, 0xffff0000, v54
	v_lshlrev_b32_e32 v113, 16, v55
	v_and_b32_e32 v124, 0xffff0000, v55
	v_fma_f32 v59, -v68, v69, 1.0
	v_fmac_f32_e32 v69, v59, v69
	v_div_scale_f32 v59, vcc, v58, v45, v58
	v_mul_f32_e32 v66, v59, v69
	v_fma_f32 v67, -v68, v66, v59
	v_fmac_f32_e32 v66, v67, v69
	v_div_scale_f32 v67, s[0:1], v44, v44, v71
	v_fma_f32 v59, -v68, v66, v59
	v_rcp_f32_e32 v68, v67
	v_div_fmas_f32 v59, v59, v69, v66
	v_div_fixup_f32 v45, v59, v45, v58
	v_mul_f32_e32 v59, 0xbfb8aa3b, v57
	v_fma_f32 v58, -v67, v68, 1.0
	v_fmac_f32_e32 v68, v58, v68
	v_mul_f32_e32 v58, 0xbfb8aa3b, v77
	v_exp_f32_e32 v58, v58
	v_exp_f32_e32 v59, v59
	v_div_scale_f32 v66, vcc, v71, v44, v71
	v_mul_f32_e32 v69, v66, v68
	v_fma_f32 v70, -v67, v69, v66
	v_fmac_f32_e32 v69, v70, v68
	v_pk_add_f32 v[58:59], v[58:59], 1.0 op_sel_hi:[1,0]
	v_fma_f32 v66, -v67, v69, v66
	v_div_scale_f32 v67, s[0:1], v59, v59, v57
	v_rcp_f32_e32 v70, v67
	v_div_fmas_f32 v66, v66, v68, v69
	v_div_fixup_f32 v44, v66, v44, v71
	v_lshlrev_b32_e32 v88, 16, v53
	v_fma_f32 v66, -v67, v70, 1.0
	v_fmac_f32_e32 v70, v66, v70
	v_div_scale_f32 v66, vcc, v57, v59, v57
	v_mul_f32_e32 v68, v66, v70
	v_fma_f32 v69, -v67, v68, v66
	v_fmac_f32_e32 v68, v69, v70
	v_fma_f32 v66, -v67, v68, v66
	v_div_scale_f32 v67, s[0:1], v58, v58, v77
	v_rcp_f32_e32 v69, v67
	v_div_fmas_f32 v66, v66, v70, v68
	v_div_fixup_f32 v57, v66, v59, v57
	v_and_b32_e32 v53, 0xffff0000, v53
	v_fma_f32 v59, -v67, v69, 1.0
	v_fmac_f32_e32 v69, v59, v69
	v_div_scale_f32 v59, vcc, v77, v58, v77
	v_mul_f32_e32 v66, v59, v69
	v_fma_f32 v68, -v67, v66, v59
	v_fmac_f32_e32 v66, v68, v69
	v_fma_f32 v59, -v67, v66, v59
	v_div_fmas_f32 v59, v59, v69, v66
	v_exp_f32_e32 v66, v56
	v_mul_f32_e32 v56, 0xbfb8aa3b, v80
	v_exp_f32_e32 v67, v56
	v_div_fixup_f32 v56, v59, v58, v77
	v_lshlrev_b32_e32 v89, 16, v52
	ds_read2_b32 v[46:47], v158 offset0:6 offset1:7
	ds_read2_b32 v[60:61], v158 offset0:4 offset1:5
	ds_read2_b32 v[62:63], v158 offset0:2 offset1:3
	ds_read2_b32 v[64:65], v158 offset1:1
	v_pk_add_f32 v[66:67], v[66:67], 1.0 op_sel_hi:[1,0]
	ds_read2_b32 v[68:69], v158 offset0:14 offset1:15
	ds_read2_b32 v[70:71], v158 offset0:12 offset1:13
	ds_read2_b32 v[72:73], v158 offset0:10 offset1:11
	ds_read2_b32 v[74:75], v158 offset0:8 offset1:9
	v_div_scale_f32 v81, s[0:1], v67, v67, v80
	v_rcp_f32_e32 v82, v81
	s_waitcnt lgkmcnt(4)
	v_add_f32_e32 v32, 0, v64
	v_add_f32_e32 v32, v32, v65
	v_add_f32_e32 v32, v32, v62
	v_fma_f32 v58, -v81, v82, 1.0
	v_fmac_f32_e32 v82, v58, v82
	v_div_scale_f32 v58, vcc, v80, v67, v80
	v_mul_f32_e32 v59, v58, v82
	v_fma_f32 v77, -v81, v59, v58
	v_fmac_f32_e32 v59, v77, v82
	v_div_scale_f32 v77, s[0:1], v66, v66, v79
	v_fma_f32 v58, -v81, v59, v58
	v_rcp_f32_e32 v81, v77
	v_div_fmas_f32 v58, v58, v82, v59
	v_div_fixup_f32 v59, v58, v67, v80
	v_add_f32_e32 v32, v32, v63
	v_fma_f32 v58, -v77, v81, 1.0
	v_fmac_f32_e32 v81, v58, v81
	v_div_scale_f32 v58, vcc, v79, v66, v79
	v_mul_f32_e32 v67, v58, v81
	v_fma_f32 v80, -v77, v67, v58
	v_fmac_f32_e32 v67, v80, v81
	v_fma_f32 v58, -v77, v67, v58
	v_div_fmas_f32 v58, v58, v81, v67
	v_div_fixup_f32 v58, v58, v66, v79
	v_mul_f32_e32 v66, 0xbfb8aa3b, v78
	v_mul_f32_e32 v67, 0xbfb8aa3b, v76
	v_exp_f32_e32 v66, v66
	v_exp_f32_e32 v67, v67
	v_add_f32_e32 v32, v32, v60
	v_add_f32_e32 v32, v32, v61
	v_add_f32_e32 v32, v32, v46
	v_pk_add_f32 v[66:67], v[66:67], 1.0 op_sel_hi:[1,0]
	v_add_f32_e32 v32, v32, v47
	v_div_scale_f32 v77, s[0:1], v67, v67, v76
	v_rcp_f32_e32 v79, v77
	s_waitcnt lgkmcnt(0)
	v_add_f32_e32 v32, v32, v74
	v_add_f32_e32 v32, v32, v75
	v_add_f32_e32 v32, v32, v72
	v_fma_f32 v80, -v77, v79, 1.0
	v_fmac_f32_e32 v79, v80, v79
	v_div_scale_f32 v80, vcc, v76, v67, v76
	v_mul_f32_e32 v81, v80, v79
	v_fma_f32 v82, -v77, v81, v80
	v_fmac_f32_e32 v81, v82, v79
	v_fma_f32 v77, -v77, v81, v80
	v_div_scale_f32 v80, s[0:1], v66, v66, v78
	v_rcp_f32_e32 v82, v80
	v_div_fmas_f32 v77, v77, v79, v81
	v_div_fixup_f32 v67, v77, v67, v76
	v_div_scale_f32 v79, vcc, v78, v66, v78
	v_fma_f32 v76, -v80, v82, 1.0
	v_fmac_f32_e32 v82, v76, v82
	v_mul_f32_e32 v81, v79, v82
	v_fma_f32 v76, -v80, v81, v79
	v_fmac_f32_e32 v81, v76, v82
	v_mul_f32_e32 v76, 0xbfb8aa3b, v83
	v_mul_f32_e32 v77, 0xbfb8aa3b, v54
	v_exp_f32_e32 v76, v76
	v_exp_f32_e32 v77, v77
	v_fma_f32 v79, -v80, v81, v79
	v_div_fmas_f32 v79, v79, v82, v81
	v_div_fixup_f32 v66, v79, v66, v78
	v_pk_add_f32 v[76:77], v[76:77], 1.0 op_sel_hi:[1,0]
	v_add_f32_e32 v32, v32, v73
	v_div_scale_f32 v80, s[0:1], v77, v77, v54
	v_rcp_f32_e32 v81, v80
	v_add_f32_e32 v32, v32, v70
	v_add_f32_e32 v32, v32, v71
	v_add_f32_e32 v32, v32, v68
	v_fma_f32 v55, -v80, v81, 1.0
	v_fmac_f32_e32 v81, v55, v81
	v_div_scale_f32 v55, vcc, v54, v77, v54
	v_mul_f32_e32 v78, v55, v81
	v_fma_f32 v79, -v80, v78, v55
	v_fmac_f32_e32 v78, v79, v81
	v_fma_f32 v55, -v80, v78, v55
	v_div_scale_f32 v80, s[0:1], v76, v76, v83
	v_rcp_f32_e32 v82, v80
	v_div_fmas_f32 v55, v55, v81, v78
	v_mul_f32_e32 v78, 0xbfb8aa3b, v88
	v_mul_f32_e32 v79, 0xbfb8aa3b, v53
	v_div_fixup_f32 v55, v55, v77, v54
	v_fma_f32 v54, -v80, v82, 1.0
	v_exp_f32_e32 v78, v78
	v_exp_f32_e32 v79, v79
	v_fmac_f32_e32 v82, v54, v82
	v_div_scale_f32 v54, vcc, v83, v76, v83
	v_mul_f32_e32 v77, v54, v82
	v_fma_f32 v81, -v80, v77, v54
	v_fmac_f32_e32 v77, v81, v82
	v_pk_add_f32 v[78:79], v[78:79], 1.0 op_sel_hi:[1,0]
	v_fma_f32 v54, -v80, v77, v54
	v_div_scale_f32 v80, s[0:1], v79, v79, v53
	v_rcp_f32_e32 v81, v80
	v_div_fmas_f32 v54, v54, v82, v77
	v_div_fixup_f32 v54, v54, v76, v83
	v_add_f32_e32 v32, v32, v69
	v_fma_f32 v76, -v80, v81, 1.0
	v_fmac_f32_e32 v81, v76, v81
	v_div_scale_f32 v76, vcc, v53, v79, v53
	v_mul_f32_e32 v77, v76, v81
	v_fma_f32 v82, -v80, v77, v76
	v_fmac_f32_e32 v77, v82, v81
	v_fma_f32 v76, -v80, v77, v76
	v_div_scale_f32 v80, s[0:1], v78, v78, v88
	v_rcp_f32_e32 v82, v80
	v_div_fmas_f32 v76, v76, v81, v77
	v_div_fixup_f32 v77, v76, v79, v53
	s_mov_b32 s37, 0
	v_fma_f32 v53, -v80, v82, 1.0
	v_fmac_f32_e32 v82, v53, v82
	v_div_scale_f32 v53, vcc, v88, v78, v88
	v_mul_f32_e32 v76, v53, v82
	v_fma_f32 v79, -v80, v76, v53
	v_fmac_f32_e32 v76, v79, v82
	v_fma_f32 v53, -v80, v76, v53
	v_and_b32_e32 v79, 0xffff0000, v52
	v_div_fmas_f32 v76, v53, v82, v76
	v_mul_f32_e32 v52, 0xbfb8aa3b, v89
	v_mul_f32_e32 v53, 0xbfb8aa3b, v79
	v_exp_f32_e32 v52, v52
	v_exp_f32_e32 v53, v53
	v_div_fixup_f32 v76, v76, v78, v88
	ds_read2_b32 v[80:81], v158 offset0:22 offset1:23
	ds_read2_b32 v[82:83], v158 offset0:20 offset1:21
	ds_read2_b32 v[84:85], v158 offset0:18 offset1:19
	ds_read2_b32 v[86:87], v158 offset0:16 offset1:17
	v_lshl_add_u64 v[34:35], v[34:35], 0, s[36:37]
	v_pk_add_f32 v[52:53], v[52:53], 1.0 op_sel_hi:[1,0]
	v_mov_b32_e32 v115, v33
	v_div_scale_f32 v90, s[0:1], v53, v53, v79
	v_rcp_f32_e32 v91, v90
	s_waitcnt lgkmcnt(0)
	v_add_f32_e32 v32, v32, v86
	v_add_f32_e32 v32, v32, v87
	v_add_f32_e32 v32, v32, v84
	v_fma_f32 v78, -v90, v91, 1.0
	v_fmac_f32_e32 v91, v78, v91
	v_div_scale_f32 v78, vcc, v79, v53, v79
	v_mul_f32_e32 v88, v78, v91
	v_fma_f32 v92, -v90, v88, v78
	v_fmac_f32_e32 v88, v92, v91
	v_fma_f32 v78, -v90, v88, v78
	v_div_scale_f32 v90, s[0:1], v52, v52, v89
	v_rcp_f32_e32 v92, v90
	v_div_fmas_f32 v78, v78, v91, v88
	v_div_fixup_f32 v79, v78, v53, v79
	v_add_f32_e32 v32, v32, v85
	v_fma_f32 v53, -v90, v92, 1.0
	v_fmac_f32_e32 v92, v53, v92
	v_div_scale_f32 v53, vcc, v89, v52, v89
	v_mul_f32_e32 v78, v53, v92
	v_fma_f32 v88, -v90, v78, v53
	v_fmac_f32_e32 v78, v88, v92
	v_fma_f32 v53, -v90, v78, v53
	v_div_fmas_f32 v53, v53, v92, v78
	v_div_fixup_f32 v78, v53, v52, v89
	v_mul_f32_e32 v52, 0xbfb8aa3b, v113
	v_mul_f32_e32 v53, 0xbfb8aa3b, v124
	v_exp_f32_e32 v52, v52
	v_exp_f32_e32 v53, v53
	v_add_f32_e32 v32, v32, v82
	v_add_f32_e32 v32, v32, v83
	v_add_f32_e32 v32, v32, v80
	v_pk_add_f32 v[88:89], v[52:53], 1.0 op_sel_hi:[1,0]
	ds_read2_b32 v[90:91], v158 offset0:30 offset1:31
	ds_read2_b32 v[52:53], v158 offset0:28 offset1:29
	ds_read2_b32 v[92:93], v158 offset0:26 offset1:27
	ds_read2_b32 v[94:95], v158 offset0:24 offset1:25
	v_add_f32_e32 v32, v32, v81
	v_div_scale_f32 v96, s[0:1], v89, v89, v124
	v_rcp_f32_e32 v132, v96
	s_waitcnt lgkmcnt(0)
	v_add_f32_e32 v32, v32, v94
	v_add_f32_e32 v32, v32, v95
	v_add_f32_e32 v32, v32, v92
	v_add_f32_e32 v32, v32, v93
	v_add_f32_e32 v32, v32, v52
	v_add_f32_e32 v32, v32, v53
	v_add_f32_e32 v32, v32, v90
	v_fma_f32 v97, -v96, v132, 1.0
	v_add_f32_e32 v32, v32, v91
	v_fmac_f32_e32 v132, v97, v132
	ds_bpermute_b32 v97, v157, v32
	v_div_scale_f32 v98, vcc, v124, v89, v124
	v_mul_f32_e32 v133, v98, v132
	v_fma_f32 v99, -v96, v133, v98
	s_waitcnt lgkmcnt(0)
	v_add_f32_e32 v32, v32, v97
	ds_bpermute_b32 v97, v156, v32
	v_fmac_f32_e32 v133, v99, v132
	v_fma_f32 v134, -v96, v133, v98
	v_lshl_add_u64 v[34:35], v[34:35], 0, v[114:115]
	v_div_scale_f32 v135, s[0:1], v88, v88, v113
	s_waitcnt lgkmcnt(0)
	v_add_f32_e32 v32, v32, v97
	v_mul_f32_e32 v32, 0x3c000000, v32
	v_pk_add_f32 v[64:65], v[64:65], v[32:33] op_sel_hi:[1,0] neg_lo:[0,1] neg_hi:[0,1]
	v_pk_add_f32 v[62:63], v[62:63], v[32:33] op_sel_hi:[1,0] neg_lo:[0,1] neg_hi:[0,1]
	v_pk_mul_f32 v[96:97], v[64:65], v[64:65]
	v_pk_mul_f32 v[98:99], v[62:63], v[62:63]
	v_pk_add_f32 v[100:101], v[60:61], v[32:33] op_sel_hi:[1,0] neg_lo:[0,1] neg_hi:[0,1]
	v_pk_add_f32 v[104:105], v[46:47], v[32:33] op_sel_hi:[1,0] neg_lo:[0,1] neg_hi:[0,1]
	v_pk_add_f32 v[74:75], v[74:75], v[32:33] op_sel_hi:[1,0] neg_lo:[0,1] neg_hi:[0,1]
	v_pk_add_f32 v[72:73], v[72:73], v[32:33] op_sel_hi:[1,0] neg_lo:[0,1] neg_hi:[0,1]
	v_pk_add_f32 v[70:71], v[70:71], v[32:33] op_sel_hi:[1,0] neg_lo:[0,1] neg_hi:[0,1]
	v_pk_add_f32 v[68:69], v[68:69], v[32:33] op_sel_hi:[1,0] neg_lo:[0,1] neg_hi:[0,1]
	v_pk_add_f32 v[86:87], v[86:87], v[32:33] op_sel_hi:[1,0] neg_lo:[0,1] neg_hi:[0,1]
	v_pk_add_f32 v[84:85], v[84:85], v[32:33] op_sel_hi:[1,0] neg_lo:[0,1] neg_hi:[0,1]
	v_pk_add_f32 v[82:83], v[82:83], v[32:33] op_sel_hi:[1,0] neg_lo:[0,1] neg_hi:[0,1]
	v_pk_add_f32 v[80:81], v[80:81], v[32:33] op_sel_hi:[1,0] neg_lo:[0,1] neg_hi:[0,1]
	v_pk_add_f32 v[94:95], v[94:95], v[32:33] op_sel_hi:[1,0] neg_lo:[0,1] neg_hi:[0,1]
	v_pk_add_f32 v[60:61], v[92:93], v[32:33] op_sel_hi:[1,0] neg_lo:[0,1] neg_hi:[0,1]
	v_pk_add_f32 v[52:53], v[52:53], v[32:33] op_sel_hi:[1,0] neg_lo:[0,1] neg_hi:[0,1]
	v_pk_add_f32 v[46:47], v[90:91], v[32:33] op_sel_hi:[1,0] neg_lo:[0,1] neg_hi:[0,1]
	v_add_f32_e32 v32, v96, v97
	v_add_f32_e32 v32, v98, v32
	v_pk_mul_f32 v[102:103], v[100:101], v[100:101]
	v_add_f32_e32 v32, v99, v32
	v_add_f32_e32 v32, v102, v32
	v_pk_mul_f32 v[106:107], v[104:105], v[104:105]
	v_add_f32_e32 v32, v103, v32
	v_add_f32_e32 v32, v106, v32
	v_pk_mul_f32 v[108:109], v[74:75], v[74:75]
	v_add_f32_e32 v32, v107, v32
	v_add_f32_e32 v32, v108, v32
	v_pk_mul_f32 v[110:111], v[72:73], v[72:73]
	v_add_f32_e32 v32, v109, v32
	v_add_f32_e32 v32, v110, v32
	v_pk_mul_f32 v[114:115], v[70:71], v[70:71]
	v_add_f32_e32 v32, v111, v32
	v_add_f32_e32 v32, v114, v32
	v_pk_mul_f32 v[116:117], v[68:69], v[68:69]
	v_add_f32_e32 v32, v115, v32
	v_add_f32_e32 v32, v116, v32
	v_pk_mul_f32 v[118:119], v[86:87], v[86:87]
	v_add_f32_e32 v32, v117, v32
	v_add_f32_e32 v32, v118, v32
	v_pk_mul_f32 v[120:121], v[84:85], v[84:85]
	v_add_f32_e32 v32, v119, v32
	v_add_f32_e32 v32, v120, v32
	v_pk_mul_f32 v[122:123], v[82:83], v[82:83]
	v_add_f32_e32 v32, v121, v32
	v_add_f32_e32 v32, v122, v32
	v_pk_mul_f32 v[126:127], v[80:81], v[80:81]
	v_add_f32_e32 v32, v123, v32
	v_add_f32_e32 v32, v126, v32
	v_pk_mul_f32 v[128:129], v[94:95], v[94:95]
	v_add_f32_e32 v32, v127, v32
	v_add_f32_e32 v32, v128, v32
	v_pk_mul_f32 v[92:93], v[60:61], v[60:61]
	v_add_f32_e32 v32, v129, v32
	v_add_f32_e32 v32, v92, v32
	v_pk_mul_f32 v[130:131], v[52:53], v[52:53]
	v_add_f32_e32 v32, v93, v32
	v_add_f32_e32 v32, v130, v32
	v_pk_mul_f32 v[90:91], v[46:47], v[46:47]
	v_add_f32_e32 v32, v131, v32
	v_add_f32_e32 v32, v90, v32
	v_add_f32_e32 v32, v91, v32
	ds_bpermute_b32 v90, v157, v32
	v_rcp_f32_e32 v136, v135
	s_mov_b32 s0, 0xf800000
	v_div_fmas_f32 v91, v134, v132, v133
	v_div_fixup_f32 v89, v91, v89, v124
	s_waitcnt lgkmcnt(0)
	v_add_f32_e32 v32, v32, v90
	ds_bpermute_b32 v90, v156, v32
	v_fma_f32 v91, -v135, v136, 1.0
	v_fmac_f32_e32 v136, v91, v136
	v_div_scale_f32 v91, vcc, v113, v88, v113
	s_waitcnt lgkmcnt(0)
	v_add_f32_e32 v32, v32, v90
	v_mov_b32_e32 v90, 0x358637bd
	v_fmac_f32_e32 v90, 0x3c000000, v32
	v_mul_f32_e32 v32, 0x4f800000, v90
	v_cmp_gt_f32_e64 s[0:1], s0, v90
	v_mul_f32_e32 v92, v91, v136
	v_fma_f32 v93, -v135, v92, v91
	v_cndmask_b32_e64 v32, v90, v32, s[0:1]
	v_sqrt_f32_e32 v90, v32
	v_fmac_f32_e32 v92, v93, v136
	v_readlane_b32 s5, v254, 1
	v_fma_f32 v91, -v135, v92, v91
	v_add_u32_e32 v93, -1, v90
	v_fma_f32 v96, -v93, v90, v32
	v_cmp_ge_f32_e64 s[4:5], 0, v96
	v_add_u32_e32 v96, 1, v90
	v_div_fmas_f32 v91, v91, v136, v92
	v_cndmask_b32_e64 v93, v90, v93, s[4:5]
	v_fma_f32 v90, -v96, v90, v32
	v_cmp_lt_f32_e64 s[4:5], 0, v90
	v_div_fixup_f32 v88, v91, v88, v113
	s_movk_i32 s2, 0x37ff
	v_cndmask_b32_e64 v90, v93, v96, s[4:5]
	v_mul_f32_e32 v93, 0x37800000, v90
	v_cndmask_b32_e64 v90, v90, v93, s[0:1]
	v_mov_b32_e32 v93, 0x260
	v_cmp_class_f32_e64 s[0:1], v32, v93
	s_nop 1
	v_cndmask_b32_e64 v32, v90, v32, s[0:1]
	v_div_scale_f32 v90, s[0:1], v32, v32, 1.0
	v_rcp_f32_e32 v93, v90
	s_nop 0
	v_fma_f32 v91, -v90, v93, 1.0
	v_fmac_f32_e32 v93, v91, v93
	v_div_scale_f32 v91, vcc, 1.0, v32, 1.0
	v_mul_f32_e32 v92, v91, v93
	v_fma_f32 v96, -v90, v92, v91
	v_fmac_f32_e32 v92, v96, v93
	v_fma_f32 v90, -v90, v92, v91
	v_div_fmas_f32 v90, v90, v93, v92
	v_div_fixup_f32 v32, v90, v32, 1.0
	v_pk_mul_f32 v[64:65], v[64:65], v[32:33] op_sel_hi:[1,0]
	s_waitcnt vmcnt(4)
	v_pk_mul_f32 v[28:29], v[28:29], v[64:65]
	s_nop 0
	v_pk_mul_f32 v[28:29], v[40:41], v[28:29]
	v_pk_mul_f32 v[40:41], v[62:63], v[32:33] op_sel_hi:[1,0]
	s_nop 0
	v_pk_mul_f32 v[30:31], v[30:31], v[40:41]
	s_nop 0
	v_pk_mul_f32 v[30:31], v[38:39], v[30:31]
	v_pk_mul_f32 v[38:39], v[100:101], v[32:33] op_sel_hi:[1,0]
	s_nop 0
	v_pk_mul_f32 v[24:25], v[24:25], v[38:39]
	s_nop 0
	v_pk_mul_f32 v[36:37], v[36:37], v[24:25]
	v_pk_mul_f32 v[24:25], v[104:105], v[32:33] op_sel_hi:[1,0]
	s_nop 0
	v_pk_mul_f32 v[24:25], v[26:27], v[24:25]
	v_cvt_pk_bf16_f32 v26, v36, v37
	v_pk_mul_f32 v[38:39], v[42:43], v[24:25]
	v_cvt_pk_bf16_f32 v24, v28, v29
	v_cvt_pk_bf16_f32 v25, v30, v31
	v_cvt_pk_bf16_f32 v27, v38, v39
	global_store_dwordx4 v[34:35], v[24:27], off
	s_nop 1
	v_pk_mul_f32 v[24:25], v[74:75], v[32:33] op_sel_hi:[1,0]
	s_nop 0
	v_pk_mul_f32 v[20:21], v[20:21], v[24:25]
	v_pk_mul_f32 v[24:25], v[72:73], v[32:33] op_sel_hi:[1,0]
	v_pk_mul_f32 v[20:21], v[58:59], v[20:21]
	v_pk_mul_f32 v[22:23], v[22:23], v[24:25]
	v_pk_mul_f32 v[24:25], v[70:71], v[32:33] op_sel_hi:[1,0]
	v_pk_mul_f32 v[22:23], v[56:57], v[22:23]
	v_pk_mul_f32 v[16:17], v[16:17], v[24:25]
	s_nop 0
	v_pk_mul_f32 v[24:25], v[44:45], v[16:17]
	v_pk_mul_f32 v[16:17], v[68:69], v[32:33] op_sel_hi:[1,0]
	s_nop 0
	v_pk_mul_f32 v[16:17], v[18:19], v[16:17]
	v_cvt_pk_bf16_f32 v18, v24, v25
	v_pk_mul_f32 v[26:27], v[66:67], v[16:17]
	v_cvt_pk_bf16_f32 v16, v20, v21
	v_cvt_pk_bf16_f32 v17, v22, v23
	v_cvt_pk_bf16_f32 v19, v26, v27
	global_store_dwordx4 v[34:35], v[16:19], off offset:16
	v_lshlrev_b32_e32 v20, 16, v48
	v_and_b32_e32 v21, 0xffff0000, v48
	v_pk_mul_f32 v[16:17], v[86:87], v[32:33] op_sel_hi:[1,0]
	s_waitcnt vmcnt(2)
	v_pk_mul_f32 v[12:13], v[12:13], v[16:17]
	v_pk_mul_f32 v[16:17], v[84:85], v[32:33] op_sel_hi:[1,0]
	v_pk_mul_f32 v[12:13], v[78:79], v[12:13]
	v_pk_mul_f32 v[14:15], v[14:15], v[16:17]
	v_pk_mul_f32 v[16:17], v[82:83], v[32:33] op_sel_hi:[1,0]
	v_pk_mul_f32 v[14:15], v[76:77], v[14:15]
	v_pk_mul_f32 v[8:9], v[8:9], v[16:17]
	s_nop 0
	v_pk_mul_f32 v[16:17], v[54:55], v[8:9]
	v_pk_mul_f32 v[8:9], v[80:81], v[32:33] op_sel_hi:[1,0]
	s_nop 0
	v_pk_mul_f32 v[8:9], v[10:11], v[8:9]
	v_mul_f32_e32 v10, 0xbfb8aa3b, v20
	v_mul_f32_e32 v11, 0xbfb8aa3b, v21
	v_exp_f32_e32 v10, v10
	v_exp_f32_e32 v11, v11
	v_pk_mul_f32 v[18:19], v[88:89], v[8:9]
	v_cvt_pk_bf16_f32 v8, v12, v13
	v_cvt_pk_bf16_f32 v9, v14, v15
	v_pk_add_f32 v[12:13], v[10:11], 1.0 op_sel_hi:[1,0]
	v_cvt_pk_bf16_f32 v10, v16, v17
	v_div_scale_f32 v14, s[0:1], v13, v13, v21
	v_rcp_f32_e32 v15, v14
	v_cvt_pk_bf16_f32 v11, v18, v19
	global_store_dwordx4 v[34:35], v[8:11], off offset:32
	v_and_b32_e32 v16, 0xffff0000, v49
	s_nop 0
	v_fma_f32 v8, -v14, v15, 1.0
	v_fmac_f32_e32 v15, v8, v15
	v_div_scale_f32 v8, vcc, v21, v13, v21
	v_mul_f32_e32 v9, v8, v15
	v_fma_f32 v10, -v14, v9, v8
	v_fmac_f32_e32 v9, v10, v15
	v_div_scale_f32 v10, s[0:1], v12, v12, v20
	v_fma_f32 v8, -v14, v9, v8
	v_rcp_f32_e32 v14, v10
	v_div_fmas_f32 v8, v8, v15, v9
	v_div_fixup_f32 v9, v8, v13, v21
	v_lshlrev_b32_e32 v15, 16, v49
	v_fma_f32 v8, -v10, v14, 1.0
	v_fmac_f32_e32 v14, v8, v14
	v_div_scale_f32 v8, vcc, v20, v12, v20
	v_mul_f32_e32 v13, v8, v14
	v_fma_f32 v11, -v10, v13, v8
	v_fmac_f32_e32 v13, v11, v14
	v_fma_f32 v8, -v10, v13, v8
	v_mul_f32_e32 v10, 0xbfb8aa3b, v15
	v_mul_f32_e32 v11, 0xbfb8aa3b, v16
	v_exp_f32_e32 v10, v10
	v_exp_f32_e32 v11, v11
	v_div_fmas_f32 v8, v8, v14, v13
	v_div_fixup_f32 v8, v8, v12, v20
	v_pk_mul_f32 v[12:13], v[94:95], v[32:33] op_sel_hi:[1,0]
	v_pk_add_f32 v[10:11], v[10:11], 1.0 op_sel_hi:[1,0]
	v_pk_mul_f32 v[4:5], v[4:5], v[12:13]
	v_div_scale_f32 v14, s[0:1], v11, v11, v16
	v_rcp_f32_e32 v17, v14
	v_pk_mul_f32 v[4:5], v[8:9], v[4:5]
	v_fma_f32 v8, -v14, v17, 1.0
	v_fmac_f32_e32 v17, v8, v17
	v_div_scale_f32 v8, vcc, v16, v11, v16
	v_mul_f32_e32 v9, v8, v17
	v_fma_f32 v12, -v14, v9, v8
	v_fmac_f32_e32 v9, v12, v17
	v_div_scale_f32 v12, s[0:1], v10, v10, v15
	v_fma_f32 v8, -v14, v9, v8
	v_rcp_f32_e32 v14, v12
	v_div_fmas_f32 v8, v8, v17, v9
	v_div_fixup_f32 v9, v8, v11, v16
	v_lshlrev_b32_e32 v16, 16, v50
	v_fma_f32 v8, -v12, v14, 1.0
	v_fmac_f32_e32 v14, v8, v14
	v_div_scale_f32 v8, vcc, v15, v10, v15
	v_mul_f32_e32 v11, v8, v14
	v_fma_f32 v13, -v12, v11, v8
	v_fmac_f32_e32 v11, v13, v14
	v_and_b32_e32 v17, 0xffff0000, v50
	v_fma_f32 v8, -v12, v11, v8
	v_mul_f32_e32 v12, 0xbfb8aa3b, v16
	v_mul_f32_e32 v13, 0xbfb8aa3b, v17
	v_exp_f32_e32 v12, v12
	v_exp_f32_e32 v13, v13
	v_div_fmas_f32 v8, v8, v14, v11
	v_div_fixup_f32 v8, v8, v10, v15
	v_pk_add_f32 v[10:11], v[12:13], 1.0 op_sel_hi:[1,0]
	s_nop 0
	v_div_scale_f32 v14, s[0:1], v11, v11, v17
	v_rcp_f32_e32 v15, v14
	v_pk_mul_f32 v[12:13], v[60:61], v[32:33] op_sel_hi:[1,0]
	s_nop 0
	v_pk_mul_f32 v[6:7], v[6:7], v[12:13]
	s_nop 0
	v_pk_mul_f32 v[6:7], v[8:9], v[6:7]
	v_fma_f32 v8, -v14, v15, 1.0
	v_fmac_f32_e32 v15, v8, v15
	v_div_scale_f32 v8, vcc, v17, v11, v17
	v_mul_f32_e32 v9, v8, v15
	v_fma_f32 v12, -v14, v9, v8
	v_fmac_f32_e32 v9, v12, v15
	v_div_scale_f32 v12, s[0:1], v10, v10, v16
	v_fma_f32 v8, -v14, v9, v8
	v_rcp_f32_e32 v14, v12
	v_div_fmas_f32 v8, v8, v15, v9
	v_div_fixup_f32 v9, v8, v11, v17
	v_lshlrev_b32_e32 v15, 16, v51
	v_fma_f32 v8, -v12, v14, 1.0
	v_fmac_f32_e32 v14, v8, v14
	v_div_scale_f32 v8, vcc, v16, v10, v16
	v_mul_f32_e32 v11, v8, v14
	v_fma_f32 v13, -v12, v11, v8
	v_fmac_f32_e32 v11, v13, v14
	v_and_b32_e32 v17, 0xffff0000, v51
	v_fma_f32 v8, -v12, v11, v8
	v_mul_f32_e32 v12, 0xbfb8aa3b, v15
	v_mul_f32_e32 v13, 0xbfb8aa3b, v17
	v_exp_f32_e32 v12, v12
	v_exp_f32_e32 v13, v13
	v_div_fmas_f32 v8, v8, v14, v11
	v_div_fixup_f32 v8, v8, v10, v16
	v_pk_add_f32 v[10:11], v[12:13], 1.0 op_sel_hi:[1,0]
	s_nop 0
	v_div_scale_f32 v14, s[0:1], v11, v11, v17
	v_rcp_f32_e32 v16, v14
	v_pk_mul_f32 v[12:13], v[52:53], v[32:33] op_sel_hi:[1,0]
	s_nop 0
	v_pk_mul_f32 v[0:1], v[0:1], v[12:13]
	s_nop 0
	v_pk_mul_f32 v[8:9], v[8:9], v[0:1]
	v_fma_f32 v0, -v14, v16, 1.0
	v_fmac_f32_e32 v16, v0, v16
	v_div_scale_f32 v0, vcc, v17, v11, v17
	v_mul_f32_e32 v1, v0, v16
	v_fma_f32 v12, -v14, v1, v0
	v_fmac_f32_e32 v1, v12, v16
	v_div_scale_f32 v12, s[0:1], v10, v10, v15
	v_rcp_f32_e32 v13, v12
	v_fma_f32 v0, -v14, v1, v0
	v_div_fmas_f32 v0, v0, v16, v1
	v_div_fixup_f32 v1, v0, v11, v17
	v_fma_f32 v0, -v12, v13, 1.0
	v_fmac_f32_e32 v13, v0, v13
	v_div_scale_f32 v0, vcc, v15, v10, v15
	v_mul_f32_e32 v11, v0, v13
	v_fma_f32 v14, -v12, v11, v0
	v_fmac_f32_e32 v11, v14, v13
	v_fma_f32 v0, -v12, v11, v0
	v_div_fmas_f32 v0, v0, v13, v11
	v_div_fixup_f32 v0, v0, v10, v15
	v_pk_mul_f32 v[10:11], v[46:47], v[32:33] op_sel_hi:[1,0]
	s_mov_b64 s[0:1], 0x3300000
	v_pk_mul_f32 v[2:3], v[2:3], v[10:11]
	s_nop 0
	v_pk_mul_f32 v[10:11], v[0:1], v[2:3]
	v_cvt_pk_bf16_f32 v0, v4, v5
	v_cvt_pk_bf16_f32 v1, v6, v7
	v_cvt_pk_bf16_f32 v2, v8, v9
	v_cvt_pk_bf16_f32 v3, v10, v11
	global_store_dwordx4 v[34:35], v[0:3], off offset:48
	v_lshl_add_u32 v5, s52, 9, v226
	s_waitcnt lgkmcnt(0)
	s_barrier
	s_lshr_b32 s0, s88, 5
	s_lshl_b32 s1, s0, 3
	s_add_i32 s1, s1, s53
	s_lshl_b32 s2, s1, 8
	s_lshl_b32 s3, s52, 3
	s_add_i32 s2, s2, s3
	v_readlane_b32 s8, v254, 2
	v_readlane_b32 s9, v254, 3
	v_lshrrev_b32_e32 v22, 6, v226
	v_add_u32_e32 v23, s2, v22
	v_and_b32_e32 v32, 63, v226
	v_lshlrev_b32_e32 v32, 4, v32
	v_bfe_u32 v33, v226, 3, 3
	v_lshlrev_b32_e32 v33, 2, v33
	v_lshl_add_u32 v0, v23, 5, v33
	v_add_u32_e32 v0, 0x3300000, v0
	v_add_u32_e32 v1, 0x1000, v0
	v_add_u32_e32 v2, 0x80000, v0
	v_add_u32_e32 v3, 0x81000, v0
	v_add_u32_e32 v4, 0x100000, v0
	v_add_u32_e32 v5, 0x101000, v0
	v_lshl_add_u32 v6, v23, 10, v32
	v_add_u32_e32 v6, 0xb500000, v6
	v_add_u32_e32 v7, s3, v22
	v_lshl_add_u32 v7, v7, 11, v32
	s_lshl_b32 s2, s1, 20
	s_add_u32 s8, s8, s2
	s_addc_u32 s9, s9, 0
	global_load_dword v60, v0, s[96:97]
	global_load_dword v61, v2, s[96:97]
	global_load_dword v62, v4, s[96:97]
	global_load_dwordx4 v[48:51], v6, s[96:97]
	v_add_u32_e32 v8, 0x1000000, v6
	global_load_dwordx4 v[52:55], v8, s[96:97]
	v_add_u32_e32 v8, 0x2000000, v6
	global_load_dwordx4 v[56:59], v8, s[96:97]
	global_load_dword v76, v0, s[96:97] offset:1024
	global_load_dword v77, v2, s[96:97] offset:1024
	global_load_dword v78, v4, s[96:97] offset:1024
	v_add_u32_e32 v8, 0x8000, v6
	global_load_dwordx4 v[64:67], v8, s[96:97]
	v_add_u32_e32 v8, 0x1008000, v6
	global_load_dwordx4 v[68:71], v8, s[96:97]
	v_add_u32_e32 v8, 0x2008000, v6
	global_load_dwordx4 v[72:75], v8, s[96:97]
	global_load_dword v92, v0, s[96:97] offset:2048
	global_load_dword v93, v2, s[96:97] offset:2048
	global_load_dword v94, v4, s[96:97] offset:2048
	v_add_u32_e32 v8, 0x10000, v6
	global_load_dwordx4 v[80:83], v8, s[96:97]
	v_add_u32_e32 v8, 0x1010000, v6
	global_load_dwordx4 v[84:87], v8, s[96:97]
	v_add_u32_e32 v8, 0x2010000, v6
	global_load_dwordx4 v[88:91], v8, s[96:97]
	global_load_dword v108, v0, s[96:97] offset:3072
	global_load_dword v109, v2, s[96:97] offset:3072
	global_load_dword v110, v4, s[96:97] offset:3072
	v_add_u32_e32 v8, 0x18000, v6
	global_load_dwordx4 v[96:99], v8, s[96:97]
	v_add_u32_e32 v8, 0x1018000, v6
	global_load_dwordx4 v[100:103], v8, s[96:97]
	v_add_u32_e32 v8, 0x2018000, v6
	global_load_dwordx4 v[104:107], v8, s[96:97]
	global_load_dword v140, v1, s[96:97]
	global_load_dword v141, v3, s[96:97]
	global_load_dword v142, v5, s[96:97]
	v_add_u32_e32 v8, 0x20000, v6
	global_load_dwordx4 v[128:131], v8, s[96:97]
	v_add_u32_e32 v8, 0x1020000, v6
	global_load_dwordx4 v[132:135], v8, s[96:97]
	v_add_u32_e32 v8, 0x2020000, v6
	global_load_dwordx4 v[136:139], v8, s[96:97]
	global_load_dword v164, v1, s[96:97] offset:1024
	global_load_dword v165, v3, s[96:97] offset:1024
	global_load_dword v166, v5, s[96:97] offset:1024
	v_add_u32_e32 v8, 0x28000, v6
	global_load_dwordx4 v[152:155], v8, s[96:97]
	v_add_u32_e32 v8, 0x1028000, v6
	global_load_dwordx4 v[156:159], v8, s[96:97]
	v_add_u32_e32 v8, 0x2028000, v6
	global_load_dwordx4 v[160:163], v8, s[96:97]
	global_load_dword v218, v1, s[96:97] offset:2048
	global_load_dword v219, v3, s[96:97] offset:2048
	global_load_dword v220, v5, s[96:97] offset:2048
	v_add_u32_e32 v8, 0x30000, v6
	global_load_dwordx4 v[206:209], v8, s[96:97]
	v_add_u32_e32 v8, 0x1030000, v6
	global_load_dwordx4 v[210:213], v8, s[96:97]
	v_add_u32_e32 v8, 0x2030000, v6
	global_load_dwordx4 v[214:217], v8, s[96:97]
	global_load_dword v244, v1, s[96:97] offset:3072
	global_load_dword v245, v3, s[96:97] offset:3072
	global_load_dword v246, v5, s[96:97] offset:3072
	v_add_u32_e32 v8, 0x38000, v6
	global_load_dwordx4 v[232:235], v8, s[96:97]
	v_add_u32_e32 v8, 0x1038000, v6
	global_load_dwordx4 v[236:239], v8, s[96:97]
	v_add_u32_e32 v8, 0x2038000, v6
	global_load_dwordx4 v[240:243], v8, s[96:97]
	s_waitcnt vmcnt(42)
	v_max3_f32 v5, v60, v61, v62
	v_sub_f32_e32 v9, v60, v5
	v_sub_f32_e32 v40, v61, v5
	v_and_b32_e32 v27, 0xffff0000, v49
	v_lshlrev_b32_e32 v28, 16, v49
	v_sub_f32_e32 v5, v62, v5
	v_lshlrev_b32_e32 v24, 16, v52
	v_and_b32_e32 v11, 0xffff0000, v52
	v_lshlrev_b32_e32 v38, 16, v56
	v_and_b32_e32 v39, 0xffff0000, v56
	v_lshlrev_b32_e32 v26, 16, v53
	v_and_b32_e32 v29, 0xffff0000, v53
	v_lshlrev_b32_e32 v14, 16, v57
	v_and_b32_e32 v15, 0xffff0000, v57
	v_lshlrev_b32_e32 v18, 16, v58
	v_and_b32_e32 v19, 0xffff0000, v58
	v_mul_f32_e32 v9, 0x3fb8aa3b, v9
	v_mul_f32_e32 v20, 0x3fb8aa3b, v40
	v_and_b32_e32 v35, 0xffff0000, v51
	v_lshlrev_b32_e32 v36, 16, v51
	v_lshlrev_b32_e32 v30, 16, v54
	v_and_b32_e32 v13, 0xffff0000, v54
	v_lshlrev_b32_e32 v34, 16, v55
	v_and_b32_e32 v37, 0xffff0000, v55
	v_lshlrev_b32_e32 v16, 16, v59
	v_and_b32_e32 v17, 0xffff0000, v59
	v_mul_f32_e32 v5, 0x3fb8aa3b, v5
	v_exp_f32_e32 v21, v9
	v_exp_f32_e32 v20, v20
	v_exp_f32_e32 v5, v5
	v_and_b32_e32 v25, 0xffff0000, v48
	v_lshlrev_b32_e32 v10, 16, v48
	v_add_f32_e32 v9, v21, v20
	v_add_f32_e32 v9, v5, v9
	v_div_scale_f32 v40, s[4:5], v9, v9, 1.0
	v_rcp_f32_e32 v42, v40
	v_div_scale_f32 v41, vcc, 1.0, v9, 1.0
	v_and_b32_e32 v31, 0xffff0000, v50
	v_fma_f32 v43, -v40, v42, 1.0
	v_fmac_f32_e32 v42, v43, v42
	v_mul_f32_e32 v43, v41, v42
	v_fma_f32 v44, -v40, v43, v41
	v_fmac_f32_e32 v43, v44, v42
	v_fma_f32 v40, -v40, v43, v41
	v_div_fmas_f32 v40, v40, v42, v43
	v_div_fixup_f32 v40, v40, v9, 1.0
	v_lshlrev_b32_e32 v12, 16, v50
	v_pk_mul_f32 v[20:21], v[20:21], v[40:41] op_sel_hi:[1,0]
	v_mul_f32_e32 v42, v5, v40
	v_pk_mul_f32 v[10:11], v[20:21], v[10:11] op_sel:[1,0] op_sel_hi:[0,1]
	v_pk_mul_f32 v[28:29], v[20:21], v[28:29] op_sel:[1,0] op_sel_hi:[0,1]
	v_pk_mul_f32 v[12:13], v[20:21], v[12:13] op_sel:[1,0] op_sel_hi:[0,1]
	v_pk_mul_f32 v[36:37], v[20:21], v[36:37] op_sel:[1,0] op_sel_hi:[0,1]
	v_pk_fma_f32 v[10:11], v[20:21], v[24:25], v[10:11]
	v_pk_fma_f32 v[24:25], v[20:21], v[26:27], v[28:29]
	v_pk_fma_f32 v[12:13], v[20:21], v[30:31], v[12:13]
	v_pk_fma_f32 v[20:21], v[20:21], v[34:35], v[36:37]
	v_pk_fma_f32 v[10:11], v[42:43], v[38:39], v[10:11] op_sel_hi:[0,1,1]
	v_pk_fma_f32 v[14:15], v[42:43], v[14:15], v[24:25] op_sel_hi:[0,1,1]
	v_pk_fma_f32 v[12:13], v[42:43], v[18:19], v[12:13] op_sel_hi:[0,1,1]
	v_pk_fma_f32 v[16:17], v[42:43], v[16:17], v[20:21] op_sel_hi:[0,1,1]
	v_cvt_pk_bf16_f32 v10, v10, v11
	v_cvt_pk_bf16_f32 v11, v14, v15
	v_cvt_pk_bf16_f32 v12, v12, v13
	v_cvt_pk_bf16_f32 v13, v16, v17
	global_store_dwordx4 v7, v[10:13], s[8:9] offset:1024
	s_waitcnt vmcnt(37)
	v_max3_f32 v5, v76, v77, v78
	v_sub_f32_e32 v9, v76, v5
	v_sub_f32_e32 v40, v77, v5
	v_and_b32_e32 v27, 0xffff0000, v65
	v_lshlrev_b32_e32 v28, 16, v65
	v_sub_f32_e32 v5, v78, v5
	v_lshlrev_b32_e32 v24, 16, v68
	v_and_b32_e32 v11, 0xffff0000, v68
	v_lshlrev_b32_e32 v38, 16, v72
	v_and_b32_e32 v39, 0xffff0000, v72
	v_lshlrev_b32_e32 v26, 16, v69
	v_and_b32_e32 v29, 0xffff0000, v69
	v_lshlrev_b32_e32 v14, 16, v73
	v_and_b32_e32 v15, 0xffff0000, v73
	v_lshlrev_b32_e32 v18, 16, v74
	v_and_b32_e32 v19, 0xffff0000, v74
	v_mul_f32_e32 v9, 0x3fb8aa3b, v9
	v_mul_f32_e32 v20, 0x3fb8aa3b, v40
	v_and_b32_e32 v35, 0xffff0000, v67
	v_lshlrev_b32_e32 v36, 16, v67
	v_lshlrev_b32_e32 v30, 16, v70
	v_and_b32_e32 v13, 0xffff0000, v70
	v_lshlrev_b32_e32 v34, 16, v71
	v_and_b32_e32 v37, 0xffff0000, v71
	v_lshlrev_b32_e32 v16, 16, v75
	v_and_b32_e32 v17, 0xffff0000, v75
	v_mul_f32_e32 v5, 0x3fb8aa3b, v5
	v_exp_f32_e32 v21, v9
	v_exp_f32_e32 v20, v20
	v_exp_f32_e32 v5, v5
	v_and_b32_e32 v25, 0xffff0000, v64
	v_lshlrev_b32_e32 v10, 16, v64
	v_add_f32_e32 v9, v21, v20
	v_add_f32_e32 v9, v5, v9
	v_div_scale_f32 v40, s[4:5], v9, v9, 1.0
	v_rcp_f32_e32 v42, v40
	v_div_scale_f32 v41, vcc, 1.0, v9, 1.0
	v_and_b32_e32 v31, 0xffff0000, v66
	v_fma_f32 v43, -v40, v42, 1.0
	v_fmac_f32_e32 v42, v43, v42
	v_mul_f32_e32 v43, v41, v42
	v_fma_f32 v44, -v40, v43, v41
	v_fmac_f32_e32 v43, v44, v42
	v_fma_f32 v40, -v40, v43, v41
	v_div_fmas_f32 v40, v40, v42, v43
	v_div_fixup_f32 v40, v40, v9, 1.0
	v_lshlrev_b32_e32 v12, 16, v66
	v_pk_mul_f32 v[20:21], v[20:21], v[40:41] op_sel_hi:[1,0]
	v_mul_f32_e32 v42, v5, v40
	v_pk_mul_f32 v[10:11], v[20:21], v[10:11] op_sel:[1,0] op_sel_hi:[0,1]
	v_pk_mul_f32 v[28:29], v[20:21], v[28:29] op_sel:[1,0] op_sel_hi:[0,1]
	v_pk_mul_f32 v[12:13], v[20:21], v[12:13] op_sel:[1,0] op_sel_hi:[0,1]
	v_pk_mul_f32 v[36:37], v[20:21], v[36:37] op_sel:[1,0] op_sel_hi:[0,1]
	v_pk_fma_f32 v[10:11], v[20:21], v[24:25], v[10:11]
	v_pk_fma_f32 v[24:25], v[20:21], v[26:27], v[28:29]
	v_pk_fma_f32 v[12:13], v[20:21], v[30:31], v[12:13]
	v_pk_fma_f32 v[20:21], v[20:21], v[34:35], v[36:37]
	v_pk_fma_f32 v[10:11], v[42:43], v[38:39], v[10:11] op_sel_hi:[0,1,1]
	v_pk_fma_f32 v[14:15], v[42:43], v[14:15], v[24:25] op_sel_hi:[0,1,1]
	v_pk_fma_f32 v[12:13], v[42:43], v[18:19], v[12:13] op_sel_hi:[0,1,1]
	v_pk_fma_f32 v[16:17], v[42:43], v[16:17], v[20:21] op_sel_hi:[0,1,1]
	v_cvt_pk_bf16_f32 v10, v10, v11
	v_cvt_pk_bf16_f32 v11, v14, v15
	v_cvt_pk_bf16_f32 v12, v12, v13
	v_cvt_pk_bf16_f32 v13, v16, v17
	v_add_u32_e32 v8, 0x10000, v7
	global_store_dwordx4 v8, v[10:13], s[8:9] offset:1024
	s_waitcnt vmcnt(32)
	v_max3_f32 v5, v92, v93, v94
	v_sub_f32_e32 v9, v92, v5
	v_sub_f32_e32 v40, v93, v5
	v_and_b32_e32 v27, 0xffff0000, v81
	v_lshlrev_b32_e32 v28, 16, v81
	v_sub_f32_e32 v5, v94, v5
	v_lshlrev_b32_e32 v24, 16, v84
	v_and_b32_e32 v11, 0xffff0000, v84
	v_lshlrev_b32_e32 v38, 16, v88
	v_and_b32_e32 v39, 0xffff0000, v88
	v_lshlrev_b32_e32 v26, 16, v85
	v_and_b32_e32 v29, 0xffff0000, v85
	v_lshlrev_b32_e32 v14, 16, v89
	v_and_b32_e32 v15, 0xffff0000, v89
	v_lshlrev_b32_e32 v18, 16, v90
	v_and_b32_e32 v19, 0xffff0000, v90
	v_mul_f32_e32 v9, 0x3fb8aa3b, v9
	v_mul_f32_e32 v20, 0x3fb8aa3b, v40
	v_and_b32_e32 v35, 0xffff0000, v83
	v_lshlrev_b32_e32 v36, 16, v83
	v_lshlrev_b32_e32 v30, 16, v86
	v_and_b32_e32 v13, 0xffff0000, v86
	v_lshlrev_b32_e32 v34, 16, v87
	v_and_b32_e32 v37, 0xffff0000, v87
	v_lshlrev_b32_e32 v16, 16, v91
	v_and_b32_e32 v17, 0xffff0000, v91
	v_mul_f32_e32 v5, 0x3fb8aa3b, v5
	v_exp_f32_e32 v21, v9
	v_exp_f32_e32 v20, v20
	v_exp_f32_e32 v5, v5
	v_and_b32_e32 v25, 0xffff0000, v80
	v_lshlrev_b32_e32 v10, 16, v80
	v_add_f32_e32 v9, v21, v20
	v_add_f32_e32 v9, v5, v9
	v_div_scale_f32 v40, s[4:5], v9, v9, 1.0
	v_rcp_f32_e32 v42, v40
	v_div_scale_f32 v41, vcc, 1.0, v9, 1.0
	v_and_b32_e32 v31, 0xffff0000, v82
	v_fma_f32 v43, -v40, v42, 1.0
	v_fmac_f32_e32 v42, v43, v42
	v_mul_f32_e32 v43, v41, v42
	v_fma_f32 v44, -v40, v43, v41
	v_fmac_f32_e32 v43, v44, v42
	v_fma_f32 v40, -v40, v43, v41
	v_div_fmas_f32 v40, v40, v42, v43
	v_div_fixup_f32 v40, v40, v9, 1.0
	v_lshlrev_b32_e32 v12, 16, v82
	v_pk_mul_f32 v[20:21], v[20:21], v[40:41] op_sel_hi:[1,0]
	v_mul_f32_e32 v42, v5, v40
	v_pk_mul_f32 v[10:11], v[20:21], v[10:11] op_sel:[1,0] op_sel_hi:[0,1]
	v_pk_mul_f32 v[28:29], v[20:21], v[28:29] op_sel:[1,0] op_sel_hi:[0,1]
	v_pk_mul_f32 v[12:13], v[20:21], v[12:13] op_sel:[1,0] op_sel_hi:[0,1]
	v_pk_mul_f32 v[36:37], v[20:21], v[36:37] op_sel:[1,0] op_sel_hi:[0,1]
	v_pk_fma_f32 v[10:11], v[20:21], v[24:25], v[10:11]
	v_pk_fma_f32 v[24:25], v[20:21], v[26:27], v[28:29]
	v_pk_fma_f32 v[12:13], v[20:21], v[30:31], v[12:13]
	v_pk_fma_f32 v[20:21], v[20:21], v[34:35], v[36:37]
	v_pk_fma_f32 v[10:11], v[42:43], v[38:39], v[10:11] op_sel_hi:[0,1,1]
	v_pk_fma_f32 v[14:15], v[42:43], v[14:15], v[24:25] op_sel_hi:[0,1,1]
	v_pk_fma_f32 v[12:13], v[42:43], v[18:19], v[12:13] op_sel_hi:[0,1,1]
	v_pk_fma_f32 v[16:17], v[42:43], v[16:17], v[20:21] op_sel_hi:[0,1,1]
	v_cvt_pk_bf16_f32 v10, v10, v11
	v_cvt_pk_bf16_f32 v11, v14, v15
	v_cvt_pk_bf16_f32 v12, v12, v13
	v_cvt_pk_bf16_f32 v13, v16, v17
	v_add_u32_e32 v8, 0x20000, v7
	global_store_dwordx4 v8, v[10:13], s[8:9] offset:1024
	s_waitcnt vmcnt(27)
	v_max3_f32 v5, v108, v109, v110
	v_sub_f32_e32 v9, v108, v5
	v_sub_f32_e32 v40, v109, v5
	v_and_b32_e32 v27, 0xffff0000, v97
	v_lshlrev_b32_e32 v28, 16, v97
	v_sub_f32_e32 v5, v110, v5
	v_lshlrev_b32_e32 v24, 16, v100
	v_and_b32_e32 v11, 0xffff0000, v100
	v_lshlrev_b32_e32 v38, 16, v104
	v_and_b32_e32 v39, 0xffff0000, v104
	v_lshlrev_b32_e32 v26, 16, v101
	v_and_b32_e32 v29, 0xffff0000, v101
	v_lshlrev_b32_e32 v14, 16, v105
	v_and_b32_e32 v15, 0xffff0000, v105
	v_lshlrev_b32_e32 v18, 16, v106
	v_and_b32_e32 v19, 0xffff0000, v106
	v_mul_f32_e32 v9, 0x3fb8aa3b, v9
	v_mul_f32_e32 v20, 0x3fb8aa3b, v40
	v_and_b32_e32 v35, 0xffff0000, v99
	v_lshlrev_b32_e32 v36, 16, v99
	v_lshlrev_b32_e32 v30, 16, v102
	v_and_b32_e32 v13, 0xffff0000, v102
	v_lshlrev_b32_e32 v34, 16, v103
	v_and_b32_e32 v37, 0xffff0000, v103
	v_lshlrev_b32_e32 v16, 16, v107
	v_and_b32_e32 v17, 0xffff0000, v107
	v_mul_f32_e32 v5, 0x3fb8aa3b, v5
	v_exp_f32_e32 v21, v9
	v_exp_f32_e32 v20, v20
	v_exp_f32_e32 v5, v5
	v_and_b32_e32 v25, 0xffff0000, v96
	v_lshlrev_b32_e32 v10, 16, v96
	v_add_f32_e32 v9, v21, v20
	v_add_f32_e32 v9, v5, v9
	v_div_scale_f32 v40, s[4:5], v9, v9, 1.0
	v_rcp_f32_e32 v42, v40
	v_div_scale_f32 v41, vcc, 1.0, v9, 1.0
	v_and_b32_e32 v31, 0xffff0000, v98
	v_fma_f32 v43, -v40, v42, 1.0
	v_fmac_f32_e32 v42, v43, v42
	v_mul_f32_e32 v43, v41, v42
	v_fma_f32 v44, -v40, v43, v41
	v_fmac_f32_e32 v43, v44, v42
	v_fma_f32 v40, -v40, v43, v41
	v_div_fmas_f32 v40, v40, v42, v43
	v_div_fixup_f32 v40, v40, v9, 1.0
	v_lshlrev_b32_e32 v12, 16, v98
	v_pk_mul_f32 v[20:21], v[20:21], v[40:41] op_sel_hi:[1,0]
	v_mul_f32_e32 v42, v5, v40
	v_pk_mul_f32 v[10:11], v[20:21], v[10:11] op_sel:[1,0] op_sel_hi:[0,1]
	v_pk_mul_f32 v[28:29], v[20:21], v[28:29] op_sel:[1,0] op_sel_hi:[0,1]
	v_pk_mul_f32 v[12:13], v[20:21], v[12:13] op_sel:[1,0] op_sel_hi:[0,1]
	v_pk_mul_f32 v[36:37], v[20:21], v[36:37] op_sel:[1,0] op_sel_hi:[0,1]
	v_pk_fma_f32 v[10:11], v[20:21], v[24:25], v[10:11]
	v_pk_fma_f32 v[24:25], v[20:21], v[26:27], v[28:29]
	v_pk_fma_f32 v[12:13], v[20:21], v[30:31], v[12:13]
	v_pk_fma_f32 v[20:21], v[20:21], v[34:35], v[36:37]
	v_pk_fma_f32 v[10:11], v[42:43], v[38:39], v[10:11] op_sel_hi:[0,1,1]
	v_pk_fma_f32 v[14:15], v[42:43], v[14:15], v[24:25] op_sel_hi:[0,1,1]
	v_pk_fma_f32 v[12:13], v[42:43], v[18:19], v[12:13] op_sel_hi:[0,1,1]
	v_pk_fma_f32 v[16:17], v[42:43], v[16:17], v[20:21] op_sel_hi:[0,1,1]
	v_cvt_pk_bf16_f32 v10, v10, v11
	v_cvt_pk_bf16_f32 v11, v14, v15
	v_cvt_pk_bf16_f32 v12, v12, v13
	v_cvt_pk_bf16_f32 v13, v16, v17
	v_add_u32_e32 v8, 0x30000, v7
	global_store_dwordx4 v8, v[10:13], s[8:9] offset:1024
	s_waitcnt vmcnt(22)
	v_max3_f32 v5, v140, v141, v142
	v_sub_f32_e32 v9, v140, v5
	v_sub_f32_e32 v40, v141, v5
	v_and_b32_e32 v27, 0xffff0000, v129
	v_lshlrev_b32_e32 v28, 16, v129
	v_sub_f32_e32 v5, v142, v5
	v_lshlrev_b32_e32 v24, 16, v132
	v_and_b32_e32 v11, 0xffff0000, v132
	v_lshlrev_b32_e32 v38, 16, v136
	v_and_b32_e32 v39, 0xffff0000, v136
	v_lshlrev_b32_e32 v26, 16, v133
	v_and_b32_e32 v29, 0xffff0000, v133
	v_lshlrev_b32_e32 v14, 16, v137
	v_and_b32_e32 v15, 0xffff0000, v137
	v_lshlrev_b32_e32 v18, 16, v138
	v_and_b32_e32 v19, 0xffff0000, v138
	v_mul_f32_e32 v9, 0x3fb8aa3b, v9
	v_mul_f32_e32 v20, 0x3fb8aa3b, v40
	v_and_b32_e32 v35, 0xffff0000, v131
	v_lshlrev_b32_e32 v36, 16, v131
	v_lshlrev_b32_e32 v30, 16, v134
	v_and_b32_e32 v13, 0xffff0000, v134
	v_lshlrev_b32_e32 v34, 16, v135
	v_and_b32_e32 v37, 0xffff0000, v135
	v_lshlrev_b32_e32 v16, 16, v139
	v_and_b32_e32 v17, 0xffff0000, v139
	v_mul_f32_e32 v5, 0x3fb8aa3b, v5
	v_exp_f32_e32 v21, v9
	v_exp_f32_e32 v20, v20
	v_exp_f32_e32 v5, v5
	v_and_b32_e32 v25, 0xffff0000, v128
	v_lshlrev_b32_e32 v10, 16, v128
	v_add_f32_e32 v9, v21, v20
	v_add_f32_e32 v9, v5, v9
	v_div_scale_f32 v40, s[4:5], v9, v9, 1.0
	v_rcp_f32_e32 v42, v40
	v_div_scale_f32 v41, vcc, 1.0, v9, 1.0
	v_and_b32_e32 v31, 0xffff0000, v130
	v_fma_f32 v43, -v40, v42, 1.0
	v_fmac_f32_e32 v42, v43, v42
	v_mul_f32_e32 v43, v41, v42
	v_fma_f32 v44, -v40, v43, v41
	v_fmac_f32_e32 v43, v44, v42
	v_fma_f32 v40, -v40, v43, v41
	v_div_fmas_f32 v40, v40, v42, v43
	v_div_fixup_f32 v40, v40, v9, 1.0
	v_lshlrev_b32_e32 v12, 16, v130
	v_pk_mul_f32 v[20:21], v[20:21], v[40:41] op_sel_hi:[1,0]
	v_mul_f32_e32 v42, v5, v40
	v_pk_mul_f32 v[10:11], v[20:21], v[10:11] op_sel:[1,0] op_sel_hi:[0,1]
	v_pk_mul_f32 v[28:29], v[20:21], v[28:29] op_sel:[1,0] op_sel_hi:[0,1]
	v_pk_mul_f32 v[12:13], v[20:21], v[12:13] op_sel:[1,0] op_sel_hi:[0,1]
	v_pk_mul_f32 v[36:37], v[20:21], v[36:37] op_sel:[1,0] op_sel_hi:[0,1]
	v_pk_fma_f32 v[10:11], v[20:21], v[24:25], v[10:11]
	v_pk_fma_f32 v[24:25], v[20:21], v[26:27], v[28:29]
	v_pk_fma_f32 v[12:13], v[20:21], v[30:31], v[12:13]
	v_pk_fma_f32 v[20:21], v[20:21], v[34:35], v[36:37]
	v_pk_fma_f32 v[10:11], v[42:43], v[38:39], v[10:11] op_sel_hi:[0,1,1]
	v_pk_fma_f32 v[14:15], v[42:43], v[14:15], v[24:25] op_sel_hi:[0,1,1]
	v_pk_fma_f32 v[12:13], v[42:43], v[18:19], v[12:13] op_sel_hi:[0,1,1]
	v_pk_fma_f32 v[16:17], v[42:43], v[16:17], v[20:21] op_sel_hi:[0,1,1]
	v_cvt_pk_bf16_f32 v10, v10, v11
	v_cvt_pk_bf16_f32 v11, v14, v15
	v_cvt_pk_bf16_f32 v12, v12, v13
	v_cvt_pk_bf16_f32 v13, v16, v17
	v_add_u32_e32 v8, 0x40000, v7
	global_store_dwordx4 v8, v[10:13], s[8:9] offset:1024
	s_waitcnt vmcnt(17)
	v_max3_f32 v5, v164, v165, v166
	v_sub_f32_e32 v9, v164, v5
	v_sub_f32_e32 v40, v165, v5
	v_and_b32_e32 v27, 0xffff0000, v153
	v_lshlrev_b32_e32 v28, 16, v153
	v_sub_f32_e32 v5, v166, v5
	v_lshlrev_b32_e32 v24, 16, v156
	v_and_b32_e32 v11, 0xffff0000, v156
	v_lshlrev_b32_e32 v38, 16, v160
	v_and_b32_e32 v39, 0xffff0000, v160
	v_lshlrev_b32_e32 v26, 16, v157
	v_and_b32_e32 v29, 0xffff0000, v157
	v_lshlrev_b32_e32 v14, 16, v161
	v_and_b32_e32 v15, 0xffff0000, v161
	v_lshlrev_b32_e32 v18, 16, v162
	v_and_b32_e32 v19, 0xffff0000, v162
	v_mul_f32_e32 v9, 0x3fb8aa3b, v9
	v_mul_f32_e32 v20, 0x3fb8aa3b, v40
	v_and_b32_e32 v35, 0xffff0000, v155
	v_lshlrev_b32_e32 v36, 16, v155
	v_lshlrev_b32_e32 v30, 16, v158
	v_and_b32_e32 v13, 0xffff0000, v158
	v_lshlrev_b32_e32 v34, 16, v159
	v_and_b32_e32 v37, 0xffff0000, v159
	v_lshlrev_b32_e32 v16, 16, v163
	v_and_b32_e32 v17, 0xffff0000, v163
	v_mul_f32_e32 v5, 0x3fb8aa3b, v5
	v_exp_f32_e32 v21, v9
	v_exp_f32_e32 v20, v20
	v_exp_f32_e32 v5, v5
	v_and_b32_e32 v25, 0xffff0000, v152
	v_lshlrev_b32_e32 v10, 16, v152
	v_add_f32_e32 v9, v21, v20
	v_add_f32_e32 v9, v5, v9
	v_div_scale_f32 v40, s[4:5], v9, v9, 1.0
	v_rcp_f32_e32 v42, v40
	v_div_scale_f32 v41, vcc, 1.0, v9, 1.0
	v_and_b32_e32 v31, 0xffff0000, v154
	v_fma_f32 v43, -v40, v42, 1.0
	v_fmac_f32_e32 v42, v43, v42
	v_mul_f32_e32 v43, v41, v42
	v_fma_f32 v44, -v40, v43, v41
	v_fmac_f32_e32 v43, v44, v42
	v_fma_f32 v40, -v40, v43, v41
	v_div_fmas_f32 v40, v40, v42, v43
	v_div_fixup_f32 v40, v40, v9, 1.0
	v_lshlrev_b32_e32 v12, 16, v154
	v_pk_mul_f32 v[20:21], v[20:21], v[40:41] op_sel_hi:[1,0]
	v_mul_f32_e32 v42, v5, v40
	v_pk_mul_f32 v[10:11], v[20:21], v[10:11] op_sel:[1,0] op_sel_hi:[0,1]
	v_pk_mul_f32 v[28:29], v[20:21], v[28:29] op_sel:[1,0] op_sel_hi:[0,1]
	v_pk_mul_f32 v[12:13], v[20:21], v[12:13] op_sel:[1,0] op_sel_hi:[0,1]
	v_pk_mul_f32 v[36:37], v[20:21], v[36:37] op_sel:[1,0] op_sel_hi:[0,1]
	v_pk_fma_f32 v[10:11], v[20:21], v[24:25], v[10:11]
	v_pk_fma_f32 v[24:25], v[20:21], v[26:27], v[28:29]
	v_pk_fma_f32 v[12:13], v[20:21], v[30:31], v[12:13]
	v_pk_fma_f32 v[20:21], v[20:21], v[34:35], v[36:37]
	v_pk_fma_f32 v[10:11], v[42:43], v[38:39], v[10:11] op_sel_hi:[0,1,1]
	v_pk_fma_f32 v[14:15], v[42:43], v[14:15], v[24:25] op_sel_hi:[0,1,1]
	v_pk_fma_f32 v[12:13], v[42:43], v[18:19], v[12:13] op_sel_hi:[0,1,1]
	v_pk_fma_f32 v[16:17], v[42:43], v[16:17], v[20:21] op_sel_hi:[0,1,1]
	v_cvt_pk_bf16_f32 v10, v10, v11
	v_cvt_pk_bf16_f32 v11, v14, v15
	v_cvt_pk_bf16_f32 v12, v12, v13
	v_cvt_pk_bf16_f32 v13, v16, v17
	v_add_u32_e32 v8, 0x50000, v7
	global_store_dwordx4 v8, v[10:13], s[8:9] offset:1024
	s_waitcnt vmcnt(12)
	v_max3_f32 v5, v218, v219, v220
	v_sub_f32_e32 v9, v218, v5
	v_sub_f32_e32 v40, v219, v5
	v_and_b32_e32 v27, 0xffff0000, v207
	v_lshlrev_b32_e32 v28, 16, v207
	v_sub_f32_e32 v5, v220, v5
	v_lshlrev_b32_e32 v24, 16, v210
	v_and_b32_e32 v11, 0xffff0000, v210
	v_lshlrev_b32_e32 v38, 16, v214
	v_and_b32_e32 v39, 0xffff0000, v214
	v_lshlrev_b32_e32 v26, 16, v211
	v_and_b32_e32 v29, 0xffff0000, v211
	v_lshlrev_b32_e32 v14, 16, v215
	v_and_b32_e32 v15, 0xffff0000, v215
	v_lshlrev_b32_e32 v18, 16, v216
	v_and_b32_e32 v19, 0xffff0000, v216
	v_mul_f32_e32 v9, 0x3fb8aa3b, v9
	v_mul_f32_e32 v20, 0x3fb8aa3b, v40
	v_and_b32_e32 v35, 0xffff0000, v209
	v_lshlrev_b32_e32 v36, 16, v209
	v_lshlrev_b32_e32 v30, 16, v212
	v_and_b32_e32 v13, 0xffff0000, v212
	v_lshlrev_b32_e32 v34, 16, v213
	v_and_b32_e32 v37, 0xffff0000, v213
	v_lshlrev_b32_e32 v16, 16, v217
	v_and_b32_e32 v17, 0xffff0000, v217
	v_mul_f32_e32 v5, 0x3fb8aa3b, v5
	v_exp_f32_e32 v21, v9
	v_exp_f32_e32 v20, v20
	v_exp_f32_e32 v5, v5
	v_and_b32_e32 v25, 0xffff0000, v206
	v_lshlrev_b32_e32 v10, 16, v206
	v_add_f32_e32 v9, v21, v20
	v_add_f32_e32 v9, v5, v9
	v_div_scale_f32 v40, s[4:5], v9, v9, 1.0
	v_rcp_f32_e32 v42, v40
	v_div_scale_f32 v41, vcc, 1.0, v9, 1.0
	v_and_b32_e32 v31, 0xffff0000, v208
	v_fma_f32 v43, -v40, v42, 1.0
	v_fmac_f32_e32 v42, v43, v42
	v_mul_f32_e32 v43, v41, v42
	v_fma_f32 v44, -v40, v43, v41
	v_fmac_f32_e32 v43, v44, v42
	v_fma_f32 v40, -v40, v43, v41
	v_div_fmas_f32 v40, v40, v42, v43
	v_div_fixup_f32 v40, v40, v9, 1.0
	v_lshlrev_b32_e32 v12, 16, v208
	v_pk_mul_f32 v[20:21], v[20:21], v[40:41] op_sel_hi:[1,0]
	v_mul_f32_e32 v42, v5, v40
	v_pk_mul_f32 v[10:11], v[20:21], v[10:11] op_sel:[1,0] op_sel_hi:[0,1]
	v_pk_mul_f32 v[28:29], v[20:21], v[28:29] op_sel:[1,0] op_sel_hi:[0,1]
	v_pk_mul_f32 v[12:13], v[20:21], v[12:13] op_sel:[1,0] op_sel_hi:[0,1]
	v_pk_mul_f32 v[36:37], v[20:21], v[36:37] op_sel:[1,0] op_sel_hi:[0,1]
	v_pk_fma_f32 v[10:11], v[20:21], v[24:25], v[10:11]
	v_pk_fma_f32 v[24:25], v[20:21], v[26:27], v[28:29]
	v_pk_fma_f32 v[12:13], v[20:21], v[30:31], v[12:13]
	v_pk_fma_f32 v[20:21], v[20:21], v[34:35], v[36:37]
	v_pk_fma_f32 v[10:11], v[42:43], v[38:39], v[10:11] op_sel_hi:[0,1,1]
	v_pk_fma_f32 v[14:15], v[42:43], v[14:15], v[24:25] op_sel_hi:[0,1,1]
	v_pk_fma_f32 v[12:13], v[42:43], v[18:19], v[12:13] op_sel_hi:[0,1,1]
	v_pk_fma_f32 v[16:17], v[42:43], v[16:17], v[20:21] op_sel_hi:[0,1,1]
	v_cvt_pk_bf16_f32 v10, v10, v11
	v_cvt_pk_bf16_f32 v11, v14, v15
	v_cvt_pk_bf16_f32 v12, v12, v13
	v_cvt_pk_bf16_f32 v13, v16, v17
	v_add_u32_e32 v8, 0x60000, v7
	global_store_dwordx4 v8, v[10:13], s[8:9] offset:1024
	s_waitcnt vmcnt(7)
	v_max3_f32 v5, v244, v245, v246
	v_sub_f32_e32 v9, v244, v5
	v_sub_f32_e32 v40, v245, v5
	v_and_b32_e32 v27, 0xffff0000, v233
	v_lshlrev_b32_e32 v28, 16, v233
	v_sub_f32_e32 v5, v246, v5
	v_lshlrev_b32_e32 v24, 16, v236
	v_and_b32_e32 v11, 0xffff0000, v236
	v_lshlrev_b32_e32 v38, 16, v240
	v_and_b32_e32 v39, 0xffff0000, v240
	v_lshlrev_b32_e32 v26, 16, v237
	v_and_b32_e32 v29, 0xffff0000, v237
	v_lshlrev_b32_e32 v14, 16, v241
	v_and_b32_e32 v15, 0xffff0000, v241
	v_lshlrev_b32_e32 v18, 16, v242
	v_and_b32_e32 v19, 0xffff0000, v242
	v_mul_f32_e32 v9, 0x3fb8aa3b, v9
	v_mul_f32_e32 v20, 0x3fb8aa3b, v40
	v_and_b32_e32 v35, 0xffff0000, v235
	v_lshlrev_b32_e32 v36, 16, v235
	v_lshlrev_b32_e32 v30, 16, v238
	v_and_b32_e32 v13, 0xffff0000, v238
	v_lshlrev_b32_e32 v34, 16, v239
	v_and_b32_e32 v37, 0xffff0000, v239
	v_lshlrev_b32_e32 v16, 16, v243
	v_and_b32_e32 v17, 0xffff0000, v243
	v_mul_f32_e32 v5, 0x3fb8aa3b, v5
	v_exp_f32_e32 v21, v9
	v_exp_f32_e32 v20, v20
	v_exp_f32_e32 v5, v5
	v_and_b32_e32 v25, 0xffff0000, v232
	v_lshlrev_b32_e32 v10, 16, v232
	v_add_f32_e32 v9, v21, v20
	v_add_f32_e32 v9, v5, v9
	v_div_scale_f32 v40, s[4:5], v9, v9, 1.0
	v_rcp_f32_e32 v42, v40
	v_div_scale_f32 v41, vcc, 1.0, v9, 1.0
	v_and_b32_e32 v31, 0xffff0000, v234
	v_fma_f32 v43, -v40, v42, 1.0
	v_fmac_f32_e32 v42, v43, v42
	v_mul_f32_e32 v43, v41, v42
	v_fma_f32 v44, -v40, v43, v41
	v_fmac_f32_e32 v43, v44, v42
	v_fma_f32 v40, -v40, v43, v41
	v_div_fmas_f32 v40, v40, v42, v43
	v_div_fixup_f32 v40, v40, v9, 1.0
	v_lshlrev_b32_e32 v12, 16, v234
	v_pk_mul_f32 v[20:21], v[20:21], v[40:41] op_sel_hi:[1,0]
	v_mul_f32_e32 v42, v5, v40
	v_pk_mul_f32 v[10:11], v[20:21], v[10:11] op_sel:[1,0] op_sel_hi:[0,1]
	v_pk_mul_f32 v[28:29], v[20:21], v[28:29] op_sel:[1,0] op_sel_hi:[0,1]
	v_pk_mul_f32 v[12:13], v[20:21], v[12:13] op_sel:[1,0] op_sel_hi:[0,1]
	v_pk_mul_f32 v[36:37], v[20:21], v[36:37] op_sel:[1,0] op_sel_hi:[0,1]
	v_pk_fma_f32 v[10:11], v[20:21], v[24:25], v[10:11]
	v_pk_fma_f32 v[24:25], v[20:21], v[26:27], v[28:29]
	v_pk_fma_f32 v[12:13], v[20:21], v[30:31], v[12:13]
	v_pk_fma_f32 v[20:21], v[20:21], v[34:35], v[36:37]
	v_pk_fma_f32 v[10:11], v[42:43], v[38:39], v[10:11] op_sel_hi:[0,1,1]
	v_pk_fma_f32 v[14:15], v[42:43], v[14:15], v[24:25] op_sel_hi:[0,1,1]
	v_pk_fma_f32 v[12:13], v[42:43], v[18:19], v[12:13] op_sel_hi:[0,1,1]
	v_pk_fma_f32 v[16:17], v[42:43], v[16:17], v[20:21] op_sel_hi:[0,1,1]
	v_cvt_pk_bf16_f32 v10, v10, v11
	v_cvt_pk_bf16_f32 v11, v14, v15
	v_cvt_pk_bf16_f32 v12, v12, v13
	v_cvt_pk_bf16_f32 v13, v16, v17
	v_add_u32_e32 v8, 0x70000, v7
	global_store_dwordx4 v8, v[10:13], s[8:9] offset:1024
	s_waitcnt vmcnt(0)
	s_barrier
	s_mov_b64 s[0:1], exec
	v_readlane_b32 s2, v254, 29
	v_readlane_b32 s3, v254, 30
	s_and_b64 s[2:3], s[0:1], s[2:3]
	s_mov_b64 exec, s[2:3]
	s_cbranch_execz .LBB0_605
	s_andn2_b64 vcc, exec, s[42:43]
	s_cbranch_vccnz .LBB0_594
	buffer_wbl2 sc1
	s_waitcnt vmcnt(0)
	s_waitcnt vmcnt(0)
